# v60 stack plus SwiGLU epilogue fold with the store-data wait state kept (hazard-checked)
# speedup vs baseline: 1.0033x; 1.0033x over previous
; __device__ __forceinline__ void rows_rstd(const float* ssq, int row0, int fq, float (&rs)[2][4]) {
;     f32x4 p[2][4];
; #pragma unroll
;     for (int ai = 0; ai < 2; ++ai)
; #pragma unroll
;         for (int m = 0; m < 4; ++m) p[ai][m] = *(const f32x4*)(ssq + (size_t)(row0 + ai * HALF + m * 16) * 16 + 4 * fq);
; #pragma unroll
;     for (int ai = 0; ai < 2; ++ai)
; #pragma unroll
;         for (int m = 0; m < 4; ++m) { float s = (p[ai][m][0] + p[ai][m][1]) + (p[ai][m][2] + p[ai][m][3]); s += __shfl_xor(s, 16); s += __shfl_xor(s, 32); rs[ai][m] = __builtin_amdgcn_rsqf(s * (1.0f / (float)DM) + RMS_EPS); }
; }
;     __device__ __forceinline__ void operator()(const f32x4 (&acc)[2][2][4][2], const Unit& u, int wr, int wc, int fr, int fq) const {
;         const int row0 = u.pm * BM + wr * 64 + fr, col0 = u.pn * HALF + wc * 32 + 8 * fq;
;         float rsv[2][4]; rows_rstd(ssq, row0, fq, rsv);
; #pragma unroll
;         for (int ai = 0; ai < 2; ++ai)
; #pragma unroll
;             for (int m = 0; m < 4; ++m) {
;                 const int row = row0 + ai * HALF + m * 16; const float rs = rsv[ai][m], cexp = -1.4426950408889634f * rs, rs2 = rs * rs;
;                 const f32x4 g0 = acc[ai][0][m][0], g1 = acc[ai][0][m][1], u0 = acc[ai][1][m][0], u1 = acc[ai][1][m][1];
;                 const f32x4 t0 = g0 * cexp, t1 = g1 * cexp;
;                 f32x4 d0 = (f32x4){__builtin_amdgcn_exp2f(t0[0]), __builtin_amdgcn_exp2f(t0[1]), __builtin_amdgcn_exp2f(t0[2]), __builtin_amdgcn_exp2f(t0[3])} + 1.0f;
;                 f32x4 d1 = (f32x4){__builtin_amdgcn_exp2f(t1[0]), __builtin_amdgcn_exp2f(t1[1]), __builtin_amdgcn_exp2f(t1[2]), __builtin_amdgcn_exp2f(t1[3])} + 1.0f;
;                 const f32x4 r0 = (f32x4){__builtin_amdgcn_rcpf(d0[0]), __builtin_amdgcn_rcpf(d0[1]), __builtin_amdgcn_rcpf(d0[2]), __builtin_amdgcn_rcpf(d0[3])} * rs2;
;                 const f32x4 r1 = (f32x4){__builtin_amdgcn_rcpf(d1[0]), __builtin_amdgcn_rcpf(d1[1]), __builtin_amdgcn_rcpf(d1[2]), __builtin_amdgcn_rcpf(d1[3])} * rs2;
;                 const f32x4 a0 = (g0 * u0) * r0, a1 = (g1 * u1) * r1;
;                 u32x4 w; w.x = cvt_pk_bf16(a0[0], a0[1]); w.y = cvt_pk_bf16(a0[2], a0[3]); w.z = cvt_pk_bf16(a1[0], a1[1]); w.w = cvt_pk_bf16(a1[2], a1[3]);
;                 *(u32x4*)(O + (((size_t)(row >> 8) * (DFF / BK) + (col0 >> 6)) * BM + (row & 255)) * BK + (col0 & 63)) = w;
.Lalign2_skip0:
	s_waitcnt vmcnt(0)
	v_mov_b32_e32 v194, v163
	v_mov_b32_e32 v195, v164
	v_mov_b32_e32 v163, v165
	v_pk_add_f32 v[162:163], v[194:195], v[162:163]
	v_mov_b32_e32 v164, v167
	v_mov_b32_e32 v165, v168
	v_mov_b32_e32 v167, v169
	v_add_f32_e32 v151, v162, v163
	v_pk_add_f32 v[162:163], v[164:165], v[166:167]
	v_mov_b32_e32 v168, v171
	v_mov_b32_e32 v169, v172
	v_mov_b32_e32 v171, v173
	v_mov_b32_e32 v172, v175
	v_mov_b32_e32 v173, v176
	v_mov_b32_e32 v175, v177
	v_mov_b32_e32 v176, v179
	v_mov_b32_e32 v177, v180
	v_mov_b32_e32 v179, v181
	v_pk_add_f32 v[164:165], v[168:169], v[170:171]
	v_pk_add_f32 v[166:167], v[172:173], v[174:175]
	ds_bpermute_b32 v153, v136, v151
	v_add_f32_e32 v161, v162, v163
	v_pk_add_f32 v[168:169], v[176:177], v[178:179]
	v_add_f32_e32 v162, v164, v165
	v_add_f32_e32 v163, v166, v167
	ds_bpermute_b32 v166, v136, v161
	v_add_f32_e32 v164, v168, v169
	ds_bpermute_b32 v167, v136, v162
	ds_bpermute_b32 v168, v136, v163
	ds_bpermute_b32 v169, v136, v164
	s_waitcnt lgkmcnt(4)
	v_add_f32_e32 v151, v151, v153
	ds_bpermute_b32 v153, v149, v151
	s_waitcnt lgkmcnt(4)
	v_add_f32_e32 v161, v161, v166
	s_waitcnt lgkmcnt(3)
	v_add_f32_e32 v162, v162, v167
	s_waitcnt lgkmcnt(2)
	v_add_f32_e32 v163, v163, v168
	ds_bpermute_b32 v166, v149, v161
	v_mov_b32_e32 v180, v183
	v_mov_b32_e32 v181, v184
	v_mov_b32_e32 v183, v185
	s_waitcnt lgkmcnt(2)
	v_add_f32_e32 v164, v164, v169
	ds_bpermute_b32 v167, v149, v162
	ds_bpermute_b32 v168, v149, v163
	v_pk_add_f32 v[170:171], v[180:181], v[182:183]
	ds_bpermute_b32 v169, v149, v164
	v_add_f32_e32 v165, v170, v171
	ds_bpermute_b32 v170, v136, v165
	s_waitcnt lgkmcnt(5)
	v_add_f32_e32 v151, v151, v153
	v_fmamk_f32 v232, v151, 0x3a800000, v160
	v_mov_b32_e32 v233, v232
	s_waitcnt lgkmcnt(4)
	v_add_f32_e32 v153, v161, v166
	s_waitcnt lgkmcnt(3)
	v_add_f32_e32 v161, v162, v167
	s_waitcnt lgkmcnt(2)
	v_add_f32_e32 v162, v163, v168
	v_rsq_f32_e32 v166, v232
	v_fmamk_f32 v234, v153, 0x3a800000, v160
	v_mov_b32_e32 v235, v234
	v_fmamk_f32 v238, v161, 0x3a800000, v160
	v_mov_b32_e32 v239, v238
	v_fmamk_f32 v240, v162, 0x3a800000, v160
	v_mov_b32_e32 v241, v240
	v_rsq_f32_e32 v172, v234
	s_waitcnt lgkmcnt(1)
	v_add_f32_e32 v151, v164, v169
	v_mov_b32_e32 v162, v187
	v_mov_b32_e32 v163, v188
	v_mov_b32_e32 v187, v189
	v_fmamk_f32 v236, v151, 0x3a800000, v160
	v_mov_b32_e32 v237, v236
	v_pk_add_f32 v[162:163], v[162:163], v[186:187]
	v_rsq_f32_e32 v173, v236
	s_waitcnt lgkmcnt(0)
	v_add_f32_e32 v151, v165, v170
	v_add_f32_e32 v165, v162, v163
	v_mov_b32_e32 v162, v191
	v_mov_b32_e32 v163, v192
	v_mov_b32_e32 v191, v193
	v_pk_add_f32 v[162:163], v[162:163], v[190:191]
	ds_bpermute_b32 v167, v136, v165
	v_add_f32_e32 v162, v162, v163
	ds_bpermute_b32 v136, v136, v162
	ds_bpermute_b32 v164, v149, v151
	v_rsq_f32_e32 v153, v238
	s_waitcnt lgkmcnt(2)
	v_add_f32_e32 v163, v165, v167
	v_rsq_f32_e32 v161, v240
	s_waitcnt lgkmcnt(1)
	v_add_f32_e32 v136, v162, v136
	s_waitcnt lgkmcnt(0)
	v_add_f32_e32 v151, v151, v164
	ds_bpermute_b32 v164, v149, v163
	ds_bpermute_b32 v149, v149, v136
	v_fmamk_f32 v242, v151, 0x3a800000, v160
	v_mov_b32_e32 v243, v242
	v_rsq_f32_e32 v174, v242
	s_waitcnt lgkmcnt(1)
	v_add_f32_e32 v151, v163, v164
	s_waitcnt lgkmcnt(0)
	v_add_f32_e32 v136, v136, v149
	v_fmamk_f32 v244, v151, 0x3a800000, v160
	v_mov_b32_e32 v245, v244
	v_fmamk_f32 v246, v136, 0x3a800000, v160
	v_mov_b32_e32 v247, v246
	v_rsq_f32_e32 v175, v244
	v_rsq_f32_e32 v151, v246
	v_mul_f32_e32 v136, 0xbfb8aa3b, v166
	v_pk_mul_f32 v[166:167], v[124:125], v[136:137] op_sel_hi:[1,0]
	v_pk_mul_f32 v[164:165], v[126:127], v[136:137] op_sel_hi:[1,0]
	v_pk_mul_f32 v[168:169], v[122:123], v[136:137] op_sel_hi:[1,0]
	v_pk_mul_f32 v[170:171], v[120:121], v[136:137] op_sel_hi:[1,0]
	v_exp_f32_e32 v166, v166
	v_exp_f32_e32 v167, v167
	v_exp_f32_e32 v164, v164
	v_exp_f32_e32 v165, v165
	v_exp_f32_e32 v170, v170
	v_exp_f32_e32 v168, v168
	v_exp_f32_e32 v169, v169
	v_exp_f32_e32 v171, v171
	v_pk_fma_f32 v[166:167], v[166:167], v[232:233], v[232:233]
	v_pk_fma_f32 v[164:165], v[164:165], v[232:233], v[232:233]
	v_pk_fma_f32 v[168:169], v[168:169], v[232:233], v[232:233]
	v_pk_fma_f32 v[170:171], v[170:171], v[232:233], v[232:233]
	v_rcp_f32_e32 v166, v166
	v_rcp_f32_e32 v167, v167
	v_rcp_f32_e32 v164, v164
	v_rcp_f32_e32 v165, v165
	v_rcp_f32_e32 v170, v170
	v_rcp_f32_e32 v171, v171
	v_rcp_f32_e32 v168, v168
	v_rcp_f32_e32 v169, v169
	s_nop 0
	v_pk_mul_f32 v[116:117], v[116:117], v[166:167]
	v_pk_mul_f32 v[120:121], v[114:115], v[168:169]
	v_pk_mul_f32 v[114:115], v[112:113], v[170:171]
	v_cvt_pk_bf16_f32 v112, v116, v117
	v_lshlrev_b32_e32 v116, 7, v152
	v_and_b32_e32 v136, 0x6780, v116
	v_pk_mul_f32 v[118:119], v[118:119], v[164:165]
	v_lshl_add_u64 v[116:117], s[60:61], 0, v[136:137]
	v_mov_b32_e32 v149, v137
	v_cvt_pk_bf16_f32 v113, v118, v119
	v_cvt_pk_bf16_f32 v114, v114, v115
	v_cvt_pk_bf16_f32 v115, v120, v121
	v_lshl_add_u64 v[116:117], v[116:117], 0, v[148:149]
	global_store_dwordx4 v[116:117], v[112:115], off
	s_nop 1
	v_mul_f32_e32 v112, 0xbfb8aa3b, v172
	v_pk_mul_f32 v[118:119], v[110:111], v[112:113] op_sel_hi:[1,0]
	v_pk_mul_f32 v[120:121], v[108:109], v[112:113] op_sel_hi:[1,0]
	v_pk_mul_f32 v[122:123], v[106:107], v[112:113] op_sel_hi:[1,0]
	v_pk_mul_f32 v[112:113], v[104:105], v[112:113] op_sel_hi:[1,0]
	v_exp_f32_e32 v120, v120
	v_exp_f32_e32 v121, v121
	v_exp_f32_e32 v118, v118
	v_exp_f32_e32 v119, v119
	v_exp_f32_e32 v112, v112
	v_exp_f32_e32 v122, v122
	v_exp_f32_e32 v123, v123
	v_exp_f32_e32 v113, v113
	v_pk_fma_f32 v[118:119], v[118:119], v[234:235], v[234:235]
	v_pk_fma_f32 v[120:121], v[120:121], v[234:235], v[234:235]
; __device__ __forceinline__ unsigned cvt_pk_bf16(float lo, float hi) { typedef float f2 __attribute__((ext_vector_type(2))); const bf16v2 r = __builtin_convertvector((f2){lo, hi}, bf16v2); return __builtin_bit_cast(unsigned, r); }
;     __device__ __forceinline__ void operator()(const f32x4 (&acc)[2][2][4][2], const Unit& u, int wr, int wc, int fr, int fq) const {
;     ...
;                 const int row = row0 + ai * HALF + m * 16; const float rs = rsv[ai][m], cexp = -1.4426950408889634f * rs, rs2 = rs * rs;
;                 const f32x4 g0 = acc[ai][0][m][0], g1 = acc[ai][0][m][1], u0 = acc[ai][1][m][0], u1 = acc[ai][1][m][1];
;                 const f32x4 t0 = g0 * cexp, t1 = g1 * cexp;
;                 f32x4 d0 = (f32x4){__builtin_amdgcn_exp2f(t0[0]), __builtin_amdgcn_exp2f(t0[1]), __builtin_amdgcn_exp2f(t0[2]), __builtin_amdgcn_exp2f(t0[3])} + 1.0f;
;                 f32x4 d1 = (f32x4){__builtin_amdgcn_exp2f(t1[0]), __builtin_amdgcn_exp2f(t1[1]), __builtin_amdgcn_exp2f(t1[2]), __builtin_amdgcn_exp2f(t1[3])} + 1.0f;
;                 const f32x4 r0 = (f32x4){__builtin_amdgcn_rcpf(d0[0]), __builtin_amdgcn_rcpf(d0[1]), __builtin_amdgcn_rcpf(d0[2]), __builtin_amdgcn_rcpf(d0[3])} * rs2;
;                 const f32x4 r1 = (f32x4){__builtin_amdgcn_rcpf(d1[0]), __builtin_amdgcn_rcpf(d1[1]), __builtin_amdgcn_rcpf(d1[2]), __builtin_amdgcn_rcpf(d1[3])} * rs2;
;                 const f32x4 a0 = (g0 * u0) * r0, a1 = (g1 * u1) * r1;
;                 u32x4 w; w.x = cvt_pk_bf16(a0[0], a0[1]); w.y = cvt_pk_bf16(a0[2], a0[3]); w.z = cvt_pk_bf16(a1[0], a1[1]); w.w = cvt_pk_bf16(a1[2], a1[3]);
;                 *(u32x4*)(O + (((size_t)(row >> 8) * (DFF / BK) + (col0 >> 6)) * BM + (row & 255)) * BK + (col0 & 63)) = w;
	v_pk_fma_f32 v[122:123], v[122:123], v[234:235], v[234:235]
	v_pk_fma_f32 v[112:113], v[112:113], v[234:235], v[234:235]
	v_rcp_f32_e32 v120, v120
	v_rcp_f32_e32 v121, v121
	v_rcp_f32_e32 v118, v118
	v_rcp_f32_e32 v119, v119
	v_rcp_f32_e32 v112, v112
	v_rcp_f32_e32 v113, v113
	v_rcp_f32_e32 v122, v122
	v_rcp_f32_e32 v123, v123
	s_nop 0
	v_pk_mul_f32 v[102:103], v[102:103], v[118:119]
	v_pk_mul_f32 v[100:101], v[100:101], v[120:121]
	v_pk_mul_f32 v[104:105], v[98:99], v[122:123]
	v_pk_mul_f32 v[98:99], v[96:97], v[112:113]
	v_cvt_pk_bf16_f32 v96, v100, v101
	v_cvt_pk_bf16_f32 v97, v102, v103
	v_cvt_pk_bf16_f32 v98, v98, v99
	v_cvt_pk_bf16_f32 v99, v104, v105
	global_store_dwordx4 v[116:117], v[96:99], off offset:2048
	s_nop 1
	v_mul_f32_e32 v96, 0xbfb8aa3b, v153
	v_pk_mul_f32 v[102:103], v[92:93], v[96:97] op_sel_hi:[1,0]
	v_pk_mul_f32 v[100:101], v[94:95], v[96:97] op_sel_hi:[1,0]
	v_pk_mul_f32 v[104:105], v[90:91], v[96:97] op_sel_hi:[1,0]
	v_pk_mul_f32 v[96:97], v[88:89], v[96:97] op_sel_hi:[1,0]
	v_exp_f32_e32 v102, v102
	v_exp_f32_e32 v103, v103
	v_exp_f32_e32 v100, v100
	v_exp_f32_e32 v101, v101
	v_exp_f32_e32 v96, v96
	v_exp_f32_e32 v104, v104
	v_exp_f32_e32 v105, v105
	v_exp_f32_e32 v97, v97
	v_pk_fma_f32 v[102:103], v[102:103], v[238:239], v[238:239]
	v_pk_fma_f32 v[100:101], v[100:101], v[238:239], v[238:239]
	v_pk_fma_f32 v[104:105], v[104:105], v[238:239], v[238:239]
	v_pk_fma_f32 v[96:97], v[96:97], v[238:239], v[238:239]
	v_rcp_f32_e32 v102, v102
	v_rcp_f32_e32 v103, v103
	v_rcp_f32_e32 v100, v100
	v_rcp_f32_e32 v101, v101
	v_rcp_f32_e32 v96, v96
	v_rcp_f32_e32 v97, v97
	v_rcp_f32_e32 v104, v104
	v_rcp_f32_e32 v105, v105
	s_nop 0
	v_pk_mul_f32 v[84:85], v[84:85], v[102:103]
	v_pk_mul_f32 v[86:87], v[86:87], v[100:101]
	v_pk_mul_f32 v[88:89], v[82:83], v[104:105]
	v_pk_mul_f32 v[82:83], v[80:81], v[96:97]
	v_cvt_pk_bf16_f32 v80, v84, v85
	v_add_co_u32_e32 v84, vcc, s80, v116
	v_cvt_pk_bf16_f32 v81, v86, v87
	v_cvt_pk_bf16_f32 v82, v82, v83
	v_cvt_pk_bf16_f32 v83, v88, v89
	v_addc_co_u32_e32 v85, vcc, 0, v117, vcc
	global_store_dwordx4 v[84:85], v[80:83], off
	s_nop 1
	v_mul_f32_e32 v80, 0xbfb8aa3b, v161
	v_pk_mul_f32 v[86:87], v[78:79], v[80:81] op_sel_hi:[1,0]
	v_pk_mul_f32 v[88:89], v[76:77], v[80:81] op_sel_hi:[1,0]
	v_pk_mul_f32 v[90:91], v[74:75], v[80:81] op_sel_hi:[1,0]
	v_pk_mul_f32 v[80:81], v[72:73], v[80:81] op_sel_hi:[1,0]
	v_exp_f32_e32 v88, v88
	v_exp_f32_e32 v89, v89
	v_exp_f32_e32 v86, v86
	v_exp_f32_e32 v87, v87
	v_exp_f32_e32 v80, v80
	v_exp_f32_e32 v90, v90
	v_exp_f32_e32 v91, v91
	v_exp_f32_e32 v81, v81
	v_pk_fma_f32 v[86:87], v[86:87], v[240:241], v[240:241]
	v_pk_fma_f32 v[88:89], v[88:89], v[240:241], v[240:241]
	v_pk_fma_f32 v[90:91], v[90:91], v[240:241], v[240:241]
	v_pk_fma_f32 v[80:81], v[80:81], v[240:241], v[240:241]
	v_rcp_f32_e32 v88, v88
	v_rcp_f32_e32 v89, v89
	v_rcp_f32_e32 v86, v86
	v_rcp_f32_e32 v87, v87
	v_rcp_f32_e32 v80, v80
	v_rcp_f32_e32 v81, v81
	v_rcp_f32_e32 v90, v90
	v_rcp_f32_e32 v91, v91
	s_nop 0
	v_pk_mul_f32 v[70:71], v[70:71], v[86:87]
	v_pk_mul_f32 v[68:69], v[68:69], v[88:89]
	v_pk_mul_f32 v[72:73], v[66:67], v[90:91]
	v_pk_mul_f32 v[66:67], v[64:65], v[80:81]
	v_cvt_pk_bf16_f32 v64, v68, v69
	v_cvt_pk_bf16_f32 v65, v70, v71
	v_cvt_pk_bf16_f32 v66, v66, v67
	v_cvt_pk_bf16_f32 v67, v72, v73
	global_store_dwordx4 v[84:85], v[64:67], off offset:2048
	s_nop 0
	s_nop 0
	v_mul_f32_e32 v66, 0xbfb8aa3b, v173
	v_pk_mul_f32 v[70:71], v[62:63], v[66:67] op_sel_hi:[1,0]
	v_pk_mul_f32 v[72:73], v[60:61], v[66:67] op_sel_hi:[1,0]
	v_pk_mul_f32 v[74:75], v[58:59], v[66:67] op_sel_hi:[1,0]
	v_pk_mul_f32 v[66:67], v[56:57], v[66:67] op_sel_hi:[1,0]
	v_exp_f32_e32 v70, v70
	v_exp_f32_e32 v71, v71
	v_exp_f32_e32 v72, v72
	v_exp_f32_e32 v73, v73
	v_exp_f32_e32 v66, v66
	v_exp_f32_e32 v74, v74
	v_exp_f32_e32 v75, v75
	v_exp_f32_e32 v67, v67
	v_pk_fma_f32 v[70:71], v[70:71], v[236:237], v[236:237]
	v_pk_fma_f32 v[72:73], v[72:73], v[236:237], v[236:237]
	v_pk_fma_f32 v[74:75], v[74:75], v[236:237], v[236:237]
	v_pk_fma_f32 v[66:67], v[66:67], v[236:237], v[236:237]
	v_rcp_f32_e32 v70, v70
	v_rcp_f32_e32 v71, v71
	v_rcp_f32_e32 v72, v72
	v_rcp_f32_e32 v73, v73
	v_rcp_f32_e32 v66, v66
	v_rcp_f32_e32 v67, v67
	v_rcp_f32_e32 v74, v74
	v_rcp_f32_e32 v75, v75
	v_lshrrev_b32_e32 v64, 8, v150
	v_mad_i32_i24 v64, v64, 44, s41
	v_ashrrev_i32_e32 v65, 31, v64
	s_nop 0
	v_pk_mul_f32 v[54:55], v[54:55], v[70:71]
	v_lshlrev_b64 v[64:65], 15, v[64:65]
	v_pk_mul_f32 v[52:53], v[52:53], v[72:73]
; #define PG8_BAR __builtin_amdgcn_s_barrier()
;     __device__ __forceinline__ void operator()(const f32x4 (&acc)[2][2][4][2], const Unit& u, int wr, int wc, int fr, int fq) const {
;     ...
;                 const int row = row0 + ai * HALF + m * 16; const float rs = rsv[ai][m], cexp = -1.4426950408889634f * rs, rs2 = rs * rs;
;                 const f32x4 g0 = acc[ai][0][m][0], g1 = acc[ai][0][m][1], u0 = acc[ai][1][m][0], u1 = acc[ai][1][m][1];
;                 const f32x4 t0 = g0 * cexp, t1 = g1 * cexp;
;                 f32x4 d0 = (f32x4){__builtin_amdgcn_exp2f(t0[0]), __builtin_amdgcn_exp2f(t0[1]), __builtin_amdgcn_exp2f(t0[2]), __builtin_amdgcn_exp2f(t0[3])} + 1.0f;
;                 f32x4 d1 = (f32x4){__builtin_amdgcn_exp2f(t1[0]), __builtin_amdgcn_exp2f(t1[1]), __builtin_amdgcn_exp2f(t1[2]), __builtin_amdgcn_exp2f(t1[3])} + 1.0f;
;                 const f32x4 r0 = (f32x4){__builtin_amdgcn_rcpf(d0[0]), __builtin_amdgcn_rcpf(d0[1]), __builtin_amdgcn_rcpf(d0[2]), __builtin_amdgcn_rcpf(d0[3])} * rs2;
;                 const f32x4 r1 = (f32x4){__builtin_amdgcn_rcpf(d1[0]), __builtin_amdgcn_rcpf(d1[1]), __builtin_amdgcn_rcpf(d1[2]), __builtin_amdgcn_rcpf(d1[3])} * rs2;
;                 const f32x4 a0 = (g0 * u0) * r0, a1 = (g1 * u1) * r1;
;                 u32x4 w; w.x = cvt_pk_bf16(a0[0], a0[1]); w.y = cvt_pk_bf16(a0[2], a0[3]); w.z = cvt_pk_bf16(a1[0], a1[1]); w.w = cvt_pk_bf16(a1[2], a1[3]);
;                 *(u32x4*)(O + (((size_t)(row >> 8) * (DFF / BK) + (col0 >> 6)) * BM + (row & 255)) * BK + (col0 & 63)) = w;
; template <class Epi, class Sched, bool ALIGN_EPI = false, bool SP2 = false, bool ATILED = false>
; __device__ __forceinline__ void gemm_phase(PG8_LAS unsigned char* lds, const Gemm g, const Sched& S, const Epi& E) {
;     ...
;         if constexpr (ALIGN_EPI) { if (wr == 0) PG8_BAR; }
;         if constexpr (!Epi::AFTER_DRAIN) { E(acc, cur, wr, wc, fr, fq); S.done(cur); }
;         if (!has_next) break;
; #pragma unroll
;         for (int a = 0; a < 2; ++a)
; #pragma unroll
;             for (int b = 0; b < 2; ++b)
; #pragma unroll
;                 for (int m = 0; m < 4; ++m)
; #pragma unroll
;                     for (int n = 0; n < 2; ++n) acc[a][b][m][n] = (f32x4){0.f, 0.f, 0.f, 0.f};
;         cur = nxt; cA = nA; cB = nB; ++ui;
;         if constexpr (ALIGN_EPI) { if (wr == 1) PG8_BAR; }
	v_pk_mul_f32 v[56:57], v[50:51], v[74:75]
	v_pk_mul_f32 v[50:51], v[48:49], v[66:67]
	v_cvt_pk_bf16_f32 v49, v54, v55
	v_lshlrev_b32_e32 v54, 7, v150
	v_cvt_pk_bf16_f32 v48, v52, v53
	v_lshl_add_u64 v[52:53], s[36:37], 0, v[64:65]
	v_and_b32_e32 v136, 0x6780, v54
	v_lshl_add_u64 v[52:53], v[52:53], 0, v[136:137]
	v_cvt_pk_bf16_f32 v50, v50, v51
	v_cvt_pk_bf16_f32 v51, v56, v57
	v_lshl_add_u64 v[52:53], v[52:53], 0, v[148:149]
	global_store_dwordx4 v[52:53], v[48:51], off
	s_nop 1
	v_mul_f32_e32 v48, 0xbfb8aa3b, v174
	v_pk_mul_f32 v[54:55], v[46:47], v[48:49] op_sel_hi:[1,0]
	v_pk_mul_f32 v[56:57], v[44:45], v[48:49] op_sel_hi:[1,0]
	v_pk_mul_f32 v[58:59], v[42:43], v[48:49] op_sel_hi:[1,0]
	v_pk_mul_f32 v[48:49], v[40:41], v[48:49] op_sel_hi:[1,0]
	v_exp_f32_e32 v56, v56
	v_exp_f32_e32 v57, v57
	v_exp_f32_e32 v54, v54
	v_exp_f32_e32 v55, v55
	v_exp_f32_e32 v48, v48
	v_exp_f32_e32 v58, v58
	v_exp_f32_e32 v59, v59
	v_exp_f32_e32 v49, v49
	v_pk_fma_f32 v[54:55], v[54:55], v[242:243], v[242:243]
	v_pk_fma_f32 v[56:57], v[56:57], v[242:243], v[242:243]
	v_pk_fma_f32 v[58:59], v[58:59], v[242:243], v[242:243]
	v_pk_fma_f32 v[48:49], v[48:49], v[242:243], v[242:243]
	v_rcp_f32_e32 v56, v56
	v_rcp_f32_e32 v57, v57
	v_rcp_f32_e32 v54, v54
	v_rcp_f32_e32 v55, v55
	v_rcp_f32_e32 v48, v48
	v_rcp_f32_e32 v49, v49
	v_rcp_f32_e32 v58, v58
	v_rcp_f32_e32 v59, v59
	s_nop 0
	v_pk_mul_f32 v[38:39], v[38:39], v[54:55]
	v_pk_mul_f32 v[36:37], v[36:37], v[56:57]
	v_pk_mul_f32 v[40:41], v[34:35], v[58:59]
	v_pk_mul_f32 v[34:35], v[32:33], v[48:49]
	v_cvt_pk_bf16_f32 v32, v36, v37
	v_cvt_pk_bf16_f32 v33, v38, v39
	v_cvt_pk_bf16_f32 v34, v34, v35
	v_cvt_pk_bf16_f32 v35, v40, v41
	global_store_dwordx4 v[52:53], v[32:35], off offset:2048
	s_nop 1
	v_mul_f32_e32 v32, 0xbfb8aa3b, v175
	v_pk_mul_f32 v[38:39], v[28:29], v[32:33] op_sel_hi:[1,0]
	v_pk_mul_f32 v[36:37], v[30:31], v[32:33] op_sel_hi:[1,0]
	v_pk_mul_f32 v[40:41], v[26:27], v[32:33] op_sel_hi:[1,0]
	v_pk_mul_f32 v[32:33], v[24:25], v[32:33] op_sel_hi:[1,0]
	v_exp_f32_e32 v38, v38
	v_exp_f32_e32 v39, v39
	v_exp_f32_e32 v36, v36
	v_exp_f32_e32 v37, v37
	v_exp_f32_e32 v32, v32
	v_exp_f32_e32 v40, v40
	v_exp_f32_e32 v41, v41
	v_exp_f32_e32 v33, v33
	v_pk_fma_f32 v[38:39], v[38:39], v[244:245], v[244:245]
	v_pk_fma_f32 v[36:37], v[36:37], v[244:245], v[244:245]
	v_pk_fma_f32 v[40:41], v[40:41], v[244:245], v[244:245]
	v_pk_fma_f32 v[32:33], v[32:33], v[244:245], v[244:245]
	v_rcp_f32_e32 v38, v38
	v_rcp_f32_e32 v39, v39
	v_rcp_f32_e32 v36, v36
	v_rcp_f32_e32 v37, v37
	v_rcp_f32_e32 v32, v32
	v_rcp_f32_e32 v33, v33
	v_rcp_f32_e32 v40, v40
	v_rcp_f32_e32 v41, v41
	s_nop 0
	v_pk_mul_f32 v[20:21], v[20:21], v[38:39]
	v_pk_mul_f32 v[22:23], v[22:23], v[36:37]
	v_pk_mul_f32 v[24:25], v[18:19], v[40:41]
	v_pk_mul_f32 v[18:19], v[16:17], v[32:33]
	v_cvt_pk_bf16_f32 v16, v20, v21
	v_add_co_u32_e32 v20, vcc, s80, v52
	v_cvt_pk_bf16_f32 v17, v22, v23
	v_cvt_pk_bf16_f32 v18, v18, v19
	v_cvt_pk_bf16_f32 v19, v24, v25
	v_addc_co_u32_e32 v21, vcc, 0, v53, vcc
	global_store_dwordx4 v[20:21], v[16:19], off
	s_andn2_b64 vcc, exec, s[0:1]
	s_mov_b64 s[0:1], -1
	v_mul_f32_e32 v16, 0xbfb8aa3b, v151
	v_pk_mul_f32 v[22:23], v[14:15], v[16:17] op_sel_hi:[1,0]
	v_pk_mul_f32 v[24:25], v[12:13], v[16:17] op_sel_hi:[1,0]
	v_pk_mul_f32 v[26:27], v[10:11], v[16:17] op_sel_hi:[1,0]
	v_pk_mul_f32 v[16:17], v[8:9], v[16:17] op_sel_hi:[1,0]
	v_exp_f32_e32 v24, v24
	v_exp_f32_e32 v25, v25
	v_exp_f32_e32 v22, v22
	v_exp_f32_e32 v23, v23
	v_exp_f32_e32 v16, v16
	v_exp_f32_e32 v26, v26
	v_exp_f32_e32 v27, v27
	v_exp_f32_e32 v17, v17
	v_pk_fma_f32 v[22:23], v[22:23], v[246:247], v[246:247]
	v_pk_fma_f32 v[24:25], v[24:25], v[246:247], v[246:247]
	v_pk_fma_f32 v[26:27], v[26:27], v[246:247], v[246:247]
	v_pk_fma_f32 v[16:17], v[16:17], v[246:247], v[246:247]
	v_rcp_f32_e32 v24, v24
	v_rcp_f32_e32 v25, v25
	v_rcp_f32_e32 v22, v22
	v_rcp_f32_e32 v23, v23
	v_rcp_f32_e32 v16, v16
	v_rcp_f32_e32 v17, v17
	v_rcp_f32_e32 v26, v26
	v_rcp_f32_e32 v27, v27
	s_nop 0
	v_pk_mul_f32 v[6:7], v[6:7], v[22:23]
	v_pk_mul_f32 v[4:5], v[4:5], v[24:25]
	v_pk_mul_f32 v[8:9], v[2:3], v[26:27]
	v_pk_mul_f32 v[2:3], v[0:1], v[16:17]
	v_cvt_pk_bf16_f32 v0, v4, v5
	v_cvt_pk_bf16_f32 v1, v6, v7
	v_cvt_pk_bf16_f32 v2, v2, v3
	v_cvt_pk_bf16_f32 v3, v8, v9
	global_store_dwordx4 v[20:21], v[0:3], off offset:2048
	s_cbranch_vccnz .LBB0_129
	s_andn2_b64 vcc, exec, s[4:5]
	s_cbranch_vccnz .LBB0_128
	s_barrier
	s_branch .LBB0_128

; __device__ __forceinline__ void rows_rstd(const float* ssq, int row0, int fq, float (&rs)[2][4]) {
;     f32x4 p[2][4];
; #pragma unroll
;     for (int ai = 0; ai < 2; ++ai)
; #pragma unroll
;         for (int m = 0; m < 4; ++m) p[ai][m] = *(const f32x4*)(ssq + (size_t)(row0 + ai * HALF + m * 16) * 16 + 4 * fq);
; #pragma unroll
;     for (int ai = 0; ai < 2; ++ai)
; #pragma unroll
;         for (int m = 0; m < 4; ++m) { float s = (p[ai][m][0] + p[ai][m][1]) + (p[ai][m][2] + p[ai][m][3]); s += __shfl_xor(s, 16); s += __shfl_xor(s, 32); rs[ai][m] = __builtin_amdgcn_rsqf(s * (1.0f / (float)DM) + RMS_EPS); }
; }
;     __device__ __forceinline__ void operator()(const f32x4 (&acc)[2][2][4][2], const Unit& u, int wr, int wc, int fr, int fq) const {
;         const int row0 = u.pm * BM + wr * 64 + fr, col0 = u.pn * HALF + wc * 32 + 8 * fq;
;         float rsv[2][4]; rows_rstd(ssq, row0, fq, rsv);
; #pragma unroll
;         for (int ai = 0; ai < 2; ++ai)
; #pragma unroll
;             for (int m = 0; m < 4; ++m) {
;                 const int row = row0 + ai * HALF + m * 16; const float rs = rsv[ai][m], cexp = -1.4426950408889634f * rs, rs2 = rs * rs;
;                 const f32x4 g0 = acc[ai][0][m][0], g1 = acc[ai][0][m][1], u0 = acc[ai][1][m][0], u1 = acc[ai][1][m][1];
;                 const f32x4 t0 = g0 * cexp, t1 = g1 * cexp;
;                 f32x4 d0 = (f32x4){__builtin_amdgcn_exp2f(t0[0]), __builtin_amdgcn_exp2f(t0[1]), __builtin_amdgcn_exp2f(t0[2]), __builtin_amdgcn_exp2f(t0[3])} + 1.0f;
;                 f32x4 d1 = (f32x4){__builtin_amdgcn_exp2f(t1[0]), __builtin_amdgcn_exp2f(t1[1]), __builtin_amdgcn_exp2f(t1[2]), __builtin_amdgcn_exp2f(t1[3])} + 1.0f;
;                 const f32x4 r0 = (f32x4){__builtin_amdgcn_rcpf(d0[0]), __builtin_amdgcn_rcpf(d0[1]), __builtin_amdgcn_rcpf(d0[2]), __builtin_amdgcn_rcpf(d0[3])} * rs2;
;                 const f32x4 r1 = (f32x4){__builtin_amdgcn_rcpf(d1[0]), __builtin_amdgcn_rcpf(d1[1]), __builtin_amdgcn_rcpf(d1[2]), __builtin_amdgcn_rcpf(d1[3])} * rs2;
;                 const f32x4 a0 = (g0 * u0) * r0, a1 = (g1 * u1) * r1;
;                 u32x4 w; w.x = cvt_pk_bf16(a0[0], a0[1]); w.y = cvt_pk_bf16(a0[2], a0[3]); w.z = cvt_pk_bf16(a1[0], a1[1]); w.w = cvt_pk_bf16(a1[2], a1[3]);
;                 *(u32x4*)(O + (((size_t)(row >> 8) * (DFF / BK) + (col0 >> 6)) * BM + (row & 255)) * BK + (col0 & 63)) = w;
.Lalign2_skip4:
	s_waitcnt vmcnt(0)
	v_mov_b32_e32 v194, v163
	v_mov_b32_e32 v195, v164
	v_mov_b32_e32 v163, v165
	v_pk_add_f32 v[162:163], v[194:195], v[162:163]
	v_mov_b32_e32 v164, v167
	v_mov_b32_e32 v165, v168
	v_mov_b32_e32 v167, v169
	v_add_f32_e32 v151, v162, v163
	v_pk_add_f32 v[162:163], v[164:165], v[166:167]
	v_mov_b32_e32 v168, v171
	v_mov_b32_e32 v169, v172
	v_mov_b32_e32 v171, v173
	v_mov_b32_e32 v172, v175
	v_mov_b32_e32 v173, v176
	v_mov_b32_e32 v175, v177
	v_mov_b32_e32 v176, v179
	v_mov_b32_e32 v177, v180
	v_mov_b32_e32 v179, v181
	v_pk_add_f32 v[164:165], v[168:169], v[170:171]
	v_pk_add_f32 v[166:167], v[172:173], v[174:175]
	ds_bpermute_b32 v153, v136, v151
	v_add_f32_e32 v161, v162, v163
	v_pk_add_f32 v[168:169], v[176:177], v[178:179]
	v_add_f32_e32 v162, v164, v165
	v_add_f32_e32 v163, v166, v167
	ds_bpermute_b32 v166, v136, v161
	v_add_f32_e32 v164, v168, v169
	ds_bpermute_b32 v167, v136, v162
	ds_bpermute_b32 v168, v136, v163
	ds_bpermute_b32 v169, v136, v164
	s_waitcnt lgkmcnt(4)
	v_add_f32_e32 v151, v151, v153
	ds_bpermute_b32 v153, v149, v151
	s_waitcnt lgkmcnt(4)
	v_add_f32_e32 v161, v161, v166
	s_waitcnt lgkmcnt(3)
	v_add_f32_e32 v162, v162, v167
	s_waitcnt lgkmcnt(2)
	v_add_f32_e32 v163, v163, v168
	ds_bpermute_b32 v166, v149, v161
	v_mov_b32_e32 v180, v183
	v_mov_b32_e32 v181, v184
	v_mov_b32_e32 v183, v185
	s_waitcnt lgkmcnt(2)
	v_add_f32_e32 v164, v164, v169
	ds_bpermute_b32 v167, v149, v162
	ds_bpermute_b32 v168, v149, v163
	v_pk_add_f32 v[170:171], v[180:181], v[182:183]
	ds_bpermute_b32 v169, v149, v164
	v_add_f32_e32 v165, v170, v171
	ds_bpermute_b32 v170, v136, v165
	s_waitcnt lgkmcnt(5)
	v_add_f32_e32 v151, v151, v153
	v_fmamk_f32 v232, v151, 0x3a800000, v160
	v_mov_b32_e32 v233, v232
	s_waitcnt lgkmcnt(4)
	v_add_f32_e32 v153, v161, v166
	s_waitcnt lgkmcnt(3)
	v_add_f32_e32 v161, v162, v167
	s_waitcnt lgkmcnt(2)
	v_add_f32_e32 v162, v163, v168
	v_rsq_f32_e32 v166, v232
	v_fmamk_f32 v234, v153, 0x3a800000, v160
	v_mov_b32_e32 v235, v234
	v_fmamk_f32 v238, v161, 0x3a800000, v160
	v_mov_b32_e32 v239, v238
	v_fmamk_f32 v240, v162, 0x3a800000, v160
	v_mov_b32_e32 v241, v240
	v_rsq_f32_e32 v172, v234
	s_waitcnt lgkmcnt(1)
	v_add_f32_e32 v151, v164, v169
	v_mov_b32_e32 v162, v187
	v_mov_b32_e32 v163, v188
	v_mov_b32_e32 v187, v189
	v_fmamk_f32 v236, v151, 0x3a800000, v160
	v_mov_b32_e32 v237, v236
	v_pk_add_f32 v[162:163], v[162:163], v[186:187]
	v_rsq_f32_e32 v173, v236
	s_waitcnt lgkmcnt(0)
	v_add_f32_e32 v151, v165, v170
	v_add_f32_e32 v165, v162, v163
	v_mov_b32_e32 v162, v191
	v_mov_b32_e32 v163, v192
	v_mov_b32_e32 v191, v193
	v_pk_add_f32 v[162:163], v[162:163], v[190:191]
	ds_bpermute_b32 v167, v136, v165
	v_add_f32_e32 v162, v162, v163
	ds_bpermute_b32 v136, v136, v162
	ds_bpermute_b32 v164, v149, v151
	v_rsq_f32_e32 v153, v238
	s_waitcnt lgkmcnt(2)
	v_add_f32_e32 v163, v165, v167
	v_rsq_f32_e32 v161, v240
	s_waitcnt lgkmcnt(1)
	v_add_f32_e32 v136, v162, v136
	s_waitcnt lgkmcnt(0)
	v_add_f32_e32 v151, v151, v164
	ds_bpermute_b32 v164, v149, v163
	ds_bpermute_b32 v149, v149, v136
	v_fmamk_f32 v242, v151, 0x3a800000, v160
	v_mov_b32_e32 v243, v242
	v_rsq_f32_e32 v174, v242
	s_waitcnt lgkmcnt(1)
	v_add_f32_e32 v151, v163, v164
	s_waitcnt lgkmcnt(0)
	v_add_f32_e32 v136, v136, v149
	v_fmamk_f32 v244, v151, 0x3a800000, v160
	v_mov_b32_e32 v245, v244
	v_fmamk_f32 v246, v136, 0x3a800000, v160
	v_mov_b32_e32 v247, v246
	v_rsq_f32_e32 v175, v244
	v_rsq_f32_e32 v151, v246
	v_mul_f32_e32 v136, 0xbfb8aa3b, v166
	v_pk_mul_f32 v[166:167], v[124:125], v[136:137] op_sel_hi:[1,0]
	v_pk_mul_f32 v[164:165], v[126:127], v[136:137] op_sel_hi:[1,0]
	v_pk_mul_f32 v[168:169], v[122:123], v[136:137] op_sel_hi:[1,0]
	v_pk_mul_f32 v[170:171], v[120:121], v[136:137] op_sel_hi:[1,0]
	v_exp_f32_e32 v166, v166
	v_exp_f32_e32 v167, v167
	v_exp_f32_e32 v164, v164
	v_exp_f32_e32 v165, v165
	v_exp_f32_e32 v170, v170
	v_exp_f32_e32 v168, v168
	v_exp_f32_e32 v169, v169
	v_exp_f32_e32 v171, v171
	v_pk_fma_f32 v[166:167], v[166:167], v[232:233], v[232:233]
	v_pk_fma_f32 v[164:165], v[164:165], v[232:233], v[232:233]
	v_pk_fma_f32 v[168:169], v[168:169], v[232:233], v[232:233]
	v_pk_fma_f32 v[170:171], v[170:171], v[232:233], v[232:233]
	v_rcp_f32_e32 v166, v166
	v_rcp_f32_e32 v167, v167
	v_rcp_f32_e32 v164, v164
	v_rcp_f32_e32 v165, v165
	v_rcp_f32_e32 v170, v170
	v_rcp_f32_e32 v171, v171
	v_rcp_f32_e32 v168, v168
	v_rcp_f32_e32 v169, v169
	s_nop 0
	v_pk_mul_f32 v[116:117], v[116:117], v[166:167]
	v_pk_mul_f32 v[120:121], v[114:115], v[168:169]
	v_pk_mul_f32 v[114:115], v[112:113], v[170:171]
	v_cvt_pk_bf16_f32 v112, v116, v117
	v_lshlrev_b32_e32 v116, 7, v152
	v_and_b32_e32 v136, 0x6780, v116
	v_pk_mul_f32 v[118:119], v[118:119], v[164:165]
	v_lshl_add_u64 v[116:117], s[20:21], 0, v[136:137]
	v_mov_b32_e32 v149, v137
	v_cvt_pk_bf16_f32 v113, v118, v119
	v_cvt_pk_bf16_f32 v114, v114, v115
	v_cvt_pk_bf16_f32 v115, v120, v121
	v_lshl_add_u64 v[116:117], v[116:117], 0, v[148:149]
	global_store_dwordx4 v[116:117], v[112:115], off
	s_nop 1
	v_mul_f32_e32 v112, 0xbfb8aa3b, v172
	v_pk_mul_f32 v[118:119], v[110:111], v[112:113] op_sel_hi:[1,0]
	v_pk_mul_f32 v[120:121], v[108:109], v[112:113] op_sel_hi:[1,0]
	v_pk_mul_f32 v[122:123], v[106:107], v[112:113] op_sel_hi:[1,0]
	v_pk_mul_f32 v[112:113], v[104:105], v[112:113] op_sel_hi:[1,0]
	v_exp_f32_e32 v120, v120
	v_exp_f32_e32 v121, v121
	v_exp_f32_e32 v118, v118
	v_exp_f32_e32 v119, v119
	v_exp_f32_e32 v112, v112
	v_exp_f32_e32 v122, v122
	v_exp_f32_e32 v123, v123
	v_exp_f32_e32 v113, v113
	v_pk_fma_f32 v[118:119], v[118:119], v[234:235], v[234:235]
	v_pk_fma_f32 v[120:121], v[120:121], v[234:235], v[234:235]
; __device__ __forceinline__ unsigned cvt_pk_bf16(float lo, float hi) { typedef float f2 __attribute__((ext_vector_type(2))); const bf16v2 r = __builtin_convertvector((f2){lo, hi}, bf16v2); return __builtin_bit_cast(unsigned, r); }
;     __device__ __forceinline__ void operator()(const f32x4 (&acc)[2][2][4][2], const Unit& u, int wr, int wc, int fr, int fq) const {
;     ...
;                 const int row = row0 + ai * HALF + m * 16; const float rs = rsv[ai][m], cexp = -1.4426950408889634f * rs, rs2 = rs * rs;
;                 const f32x4 g0 = acc[ai][0][m][0], g1 = acc[ai][0][m][1], u0 = acc[ai][1][m][0], u1 = acc[ai][1][m][1];
;                 const f32x4 t0 = g0 * cexp, t1 = g1 * cexp;
;                 f32x4 d0 = (f32x4){__builtin_amdgcn_exp2f(t0[0]), __builtin_amdgcn_exp2f(t0[1]), __builtin_amdgcn_exp2f(t0[2]), __builtin_amdgcn_exp2f(t0[3])} + 1.0f;
;                 f32x4 d1 = (f32x4){__builtin_amdgcn_exp2f(t1[0]), __builtin_amdgcn_exp2f(t1[1]), __builtin_amdgcn_exp2f(t1[2]), __builtin_amdgcn_exp2f(t1[3])} + 1.0f;
;                 const f32x4 r0 = (f32x4){__builtin_amdgcn_rcpf(d0[0]), __builtin_amdgcn_rcpf(d0[1]), __builtin_amdgcn_rcpf(d0[2]), __builtin_amdgcn_rcpf(d0[3])} * rs2;
;                 const f32x4 r1 = (f32x4){__builtin_amdgcn_rcpf(d1[0]), __builtin_amdgcn_rcpf(d1[1]), __builtin_amdgcn_rcpf(d1[2]), __builtin_amdgcn_rcpf(d1[3])} * rs2;
;                 const f32x4 a0 = (g0 * u0) * r0, a1 = (g1 * u1) * r1;
;                 u32x4 w; w.x = cvt_pk_bf16(a0[0], a0[1]); w.y = cvt_pk_bf16(a0[2], a0[3]); w.z = cvt_pk_bf16(a1[0], a1[1]); w.w = cvt_pk_bf16(a1[2], a1[3]);
;                 *(u32x4*)(O + (((size_t)(row >> 8) * (DFF / BK) + (col0 >> 6)) * BM + (row & 255)) * BK + (col0 & 63)) = w;
	v_pk_fma_f32 v[122:123], v[122:123], v[234:235], v[234:235]
	v_pk_fma_f32 v[112:113], v[112:113], v[234:235], v[234:235]
	v_rcp_f32_e32 v120, v120
	v_rcp_f32_e32 v121, v121
	v_rcp_f32_e32 v118, v118
	v_rcp_f32_e32 v119, v119
	v_rcp_f32_e32 v112, v112
	v_rcp_f32_e32 v113, v113
	v_rcp_f32_e32 v122, v122
	v_rcp_f32_e32 v123, v123
	s_nop 0
	v_pk_mul_f32 v[102:103], v[102:103], v[118:119]
	v_pk_mul_f32 v[100:101], v[100:101], v[120:121]
	v_pk_mul_f32 v[104:105], v[98:99], v[122:123]
	v_pk_mul_f32 v[98:99], v[96:97], v[112:113]
	v_cvt_pk_bf16_f32 v96, v100, v101
	v_cvt_pk_bf16_f32 v97, v102, v103
	v_cvt_pk_bf16_f32 v98, v98, v99
	v_cvt_pk_bf16_f32 v99, v104, v105
	global_store_dwordx4 v[116:117], v[96:99], off offset:2048
	s_nop 1
	v_mul_f32_e32 v96, 0xbfb8aa3b, v153
	v_pk_mul_f32 v[102:103], v[92:93], v[96:97] op_sel_hi:[1,0]
	v_pk_mul_f32 v[100:101], v[94:95], v[96:97] op_sel_hi:[1,0]
	v_pk_mul_f32 v[104:105], v[90:91], v[96:97] op_sel_hi:[1,0]
	v_pk_mul_f32 v[96:97], v[88:89], v[96:97] op_sel_hi:[1,0]
	v_exp_f32_e32 v102, v102
	v_exp_f32_e32 v103, v103
	v_exp_f32_e32 v100, v100
	v_exp_f32_e32 v101, v101
	v_exp_f32_e32 v96, v96
	v_exp_f32_e32 v104, v104
	v_exp_f32_e32 v105, v105
	v_exp_f32_e32 v97, v97
	v_pk_fma_f32 v[102:103], v[102:103], v[238:239], v[238:239]
	v_pk_fma_f32 v[100:101], v[100:101], v[238:239], v[238:239]
	v_pk_fma_f32 v[104:105], v[104:105], v[238:239], v[238:239]
	v_pk_fma_f32 v[96:97], v[96:97], v[238:239], v[238:239]
	v_rcp_f32_e32 v102, v102
	v_rcp_f32_e32 v103, v103
	v_rcp_f32_e32 v100, v100
	v_rcp_f32_e32 v101, v101
	v_rcp_f32_e32 v96, v96
	v_rcp_f32_e32 v97, v97
	v_rcp_f32_e32 v104, v104
	v_rcp_f32_e32 v105, v105
	s_nop 0
	v_pk_mul_f32 v[84:85], v[84:85], v[102:103]
	v_pk_mul_f32 v[86:87], v[86:87], v[100:101]
	v_pk_mul_f32 v[88:89], v[82:83], v[104:105]
	v_pk_mul_f32 v[82:83], v[80:81], v[96:97]
	v_cvt_pk_bf16_f32 v80, v84, v85
	v_add_co_u32_e32 v84, vcc, s62, v116
	v_cvt_pk_bf16_f32 v81, v86, v87
	v_cvt_pk_bf16_f32 v82, v82, v83
	v_cvt_pk_bf16_f32 v83, v88, v89
	v_addc_co_u32_e32 v85, vcc, 0, v117, vcc
	global_store_dwordx4 v[84:85], v[80:83], off
	s_nop 1
	v_mul_f32_e32 v80, 0xbfb8aa3b, v161
	v_pk_mul_f32 v[86:87], v[78:79], v[80:81] op_sel_hi:[1,0]
	v_pk_mul_f32 v[88:89], v[76:77], v[80:81] op_sel_hi:[1,0]
	v_pk_mul_f32 v[90:91], v[74:75], v[80:81] op_sel_hi:[1,0]
	v_pk_mul_f32 v[80:81], v[72:73], v[80:81] op_sel_hi:[1,0]
	v_exp_f32_e32 v88, v88
	v_exp_f32_e32 v89, v89
	v_exp_f32_e32 v86, v86
	v_exp_f32_e32 v87, v87
	v_exp_f32_e32 v80, v80
	v_exp_f32_e32 v90, v90
	v_exp_f32_e32 v91, v91
	v_exp_f32_e32 v81, v81
	v_pk_fma_f32 v[86:87], v[86:87], v[240:241], v[240:241]
	v_pk_fma_f32 v[88:89], v[88:89], v[240:241], v[240:241]
	v_pk_fma_f32 v[90:91], v[90:91], v[240:241], v[240:241]
	v_pk_fma_f32 v[80:81], v[80:81], v[240:241], v[240:241]
	v_rcp_f32_e32 v88, v88
	v_rcp_f32_e32 v89, v89
	v_rcp_f32_e32 v86, v86
	v_rcp_f32_e32 v87, v87
	v_rcp_f32_e32 v80, v80
	v_rcp_f32_e32 v81, v81
	v_rcp_f32_e32 v90, v90
	v_rcp_f32_e32 v91, v91
	s_nop 0
	v_pk_mul_f32 v[70:71], v[70:71], v[86:87]
	v_pk_mul_f32 v[68:69], v[68:69], v[88:89]
	v_pk_mul_f32 v[72:73], v[66:67], v[90:91]
	v_pk_mul_f32 v[66:67], v[64:65], v[80:81]
	v_cvt_pk_bf16_f32 v64, v68, v69
	v_cvt_pk_bf16_f32 v65, v70, v71
	v_cvt_pk_bf16_f32 v66, v66, v67
	v_cvt_pk_bf16_f32 v67, v72, v73
	global_store_dwordx4 v[84:85], v[64:67], off offset:2048
	s_nop 0
	s_nop 0
	v_mul_f32_e32 v66, 0xbfb8aa3b, v173
	v_pk_mul_f32 v[70:71], v[62:63], v[66:67] op_sel_hi:[1,0]
	v_pk_mul_f32 v[72:73], v[60:61], v[66:67] op_sel_hi:[1,0]
	v_pk_mul_f32 v[74:75], v[58:59], v[66:67] op_sel_hi:[1,0]
	v_pk_mul_f32 v[66:67], v[56:57], v[66:67] op_sel_hi:[1,0]
	v_exp_f32_e32 v70, v70
	v_exp_f32_e32 v71, v71
	v_exp_f32_e32 v72, v72
	v_exp_f32_e32 v73, v73
	v_exp_f32_e32 v66, v66
	v_exp_f32_e32 v74, v74
	v_exp_f32_e32 v75, v75
	v_exp_f32_e32 v67, v67
	v_pk_fma_f32 v[70:71], v[70:71], v[236:237], v[236:237]
	v_pk_fma_f32 v[72:73], v[72:73], v[236:237], v[236:237]
	v_pk_fma_f32 v[74:75], v[74:75], v[236:237], v[236:237]
	v_pk_fma_f32 v[66:67], v[66:67], v[236:237], v[236:237]
	v_rcp_f32_e32 v70, v70
	v_rcp_f32_e32 v71, v71
	v_rcp_f32_e32 v72, v72
	v_rcp_f32_e32 v73, v73
	v_rcp_f32_e32 v66, v66
	v_rcp_f32_e32 v67, v67
	v_rcp_f32_e32 v74, v74
	v_rcp_f32_e32 v75, v75
	v_lshrrev_b32_e32 v64, 8, v150
	v_mad_i32_i24 v64, v64, 44, s11
	v_ashrrev_i32_e32 v65, 31, v64
	s_nop 0
	v_pk_mul_f32 v[54:55], v[54:55], v[70:71]
	v_lshlrev_b64 v[64:65], 15, v[64:65]
	v_pk_mul_f32 v[52:53], v[52:53], v[72:73]
; #define PG8_BAR __builtin_amdgcn_s_barrier()
;     __device__ __forceinline__ void operator()(const f32x4 (&acc)[2][2][4][2], const Unit& u, int wr, int wc, int fr, int fq) const {
;     ...
;                 const int row = row0 + ai * HALF + m * 16; const float rs = rsv[ai][m], cexp = -1.4426950408889634f * rs, rs2 = rs * rs;
;                 const f32x4 g0 = acc[ai][0][m][0], g1 = acc[ai][0][m][1], u0 = acc[ai][1][m][0], u1 = acc[ai][1][m][1];
;                 const f32x4 t0 = g0 * cexp, t1 = g1 * cexp;
;                 f32x4 d0 = (f32x4){__builtin_amdgcn_exp2f(t0[0]), __builtin_amdgcn_exp2f(t0[1]), __builtin_amdgcn_exp2f(t0[2]), __builtin_amdgcn_exp2f(t0[3])} + 1.0f;
;                 f32x4 d1 = (f32x4){__builtin_amdgcn_exp2f(t1[0]), __builtin_amdgcn_exp2f(t1[1]), __builtin_amdgcn_exp2f(t1[2]), __builtin_amdgcn_exp2f(t1[3])} + 1.0f;
;                 const f32x4 r0 = (f32x4){__builtin_amdgcn_rcpf(d0[0]), __builtin_amdgcn_rcpf(d0[1]), __builtin_amdgcn_rcpf(d0[2]), __builtin_amdgcn_rcpf(d0[3])} * rs2;
;                 const f32x4 r1 = (f32x4){__builtin_amdgcn_rcpf(d1[0]), __builtin_amdgcn_rcpf(d1[1]), __builtin_amdgcn_rcpf(d1[2]), __builtin_amdgcn_rcpf(d1[3])} * rs2;
;                 const f32x4 a0 = (g0 * u0) * r0, a1 = (g1 * u1) * r1;
;                 u32x4 w; w.x = cvt_pk_bf16(a0[0], a0[1]); w.y = cvt_pk_bf16(a0[2], a0[3]); w.z = cvt_pk_bf16(a1[0], a1[1]); w.w = cvt_pk_bf16(a1[2], a1[3]);
;                 *(u32x4*)(O + (((size_t)(row >> 8) * (DFF / BK) + (col0 >> 6)) * BM + (row & 255)) * BK + (col0 & 63)) = w;
; template <class Epi, class Sched, bool ALIGN_EPI = false, bool SP2 = false, bool ATILED = false>
; __device__ __forceinline__ void gemm_phase(PG8_LAS unsigned char* lds, const Gemm g, const Sched& S, const Epi& E) {
;     ...
;         if constexpr (ALIGN_EPI) { if (wr == 0) PG8_BAR; }
;         if constexpr (!Epi::AFTER_DRAIN) { E(acc, cur, wr, wc, fr, fq); S.done(cur); }
;         if (!has_next) break;
; #pragma unroll
;         for (int a = 0; a < 2; ++a)
; #pragma unroll
;             for (int b = 0; b < 2; ++b)
; #pragma unroll
;                 for (int m = 0; m < 4; ++m)
; #pragma unroll
;                     for (int n = 0; n < 2; ++n) acc[a][b][m][n] = (f32x4){0.f, 0.f, 0.f, 0.f};
;         cur = nxt; cA = nA; cB = nB; ++ui;
;         if constexpr (ALIGN_EPI) { if (wr == 1) PG8_BAR; }
	v_pk_mul_f32 v[56:57], v[50:51], v[74:75]
	v_pk_mul_f32 v[50:51], v[48:49], v[66:67]
	v_cvt_pk_bf16_f32 v49, v54, v55
	v_lshlrev_b32_e32 v54, 7, v150
	v_cvt_pk_bf16_f32 v48, v52, v53
	v_lshl_add_u64 v[52:53], s[36:37], 0, v[64:65]
	v_and_b32_e32 v136, 0x6780, v54
	v_lshl_add_u64 v[52:53], v[52:53], 0, v[136:137]
	v_cvt_pk_bf16_f32 v50, v50, v51
	v_cvt_pk_bf16_f32 v51, v56, v57
	v_lshl_add_u64 v[52:53], v[52:53], 0, v[148:149]
	global_store_dwordx4 v[52:53], v[48:51], off
	s_nop 1
	v_mul_f32_e32 v48, 0xbfb8aa3b, v174
	v_pk_mul_f32 v[54:55], v[46:47], v[48:49] op_sel_hi:[1,0]
	v_pk_mul_f32 v[56:57], v[44:45], v[48:49] op_sel_hi:[1,0]
	v_pk_mul_f32 v[58:59], v[42:43], v[48:49] op_sel_hi:[1,0]
	v_pk_mul_f32 v[48:49], v[40:41], v[48:49] op_sel_hi:[1,0]
	v_exp_f32_e32 v56, v56
	v_exp_f32_e32 v57, v57
	v_exp_f32_e32 v54, v54
	v_exp_f32_e32 v55, v55
	v_exp_f32_e32 v48, v48
	v_exp_f32_e32 v58, v58
	v_exp_f32_e32 v59, v59
	v_exp_f32_e32 v49, v49
	v_pk_fma_f32 v[54:55], v[54:55], v[242:243], v[242:243]
	v_pk_fma_f32 v[56:57], v[56:57], v[242:243], v[242:243]
	v_pk_fma_f32 v[58:59], v[58:59], v[242:243], v[242:243]
	v_pk_fma_f32 v[48:49], v[48:49], v[242:243], v[242:243]
	v_rcp_f32_e32 v56, v56
	v_rcp_f32_e32 v57, v57
	v_rcp_f32_e32 v54, v54
	v_rcp_f32_e32 v55, v55
	v_rcp_f32_e32 v48, v48
	v_rcp_f32_e32 v49, v49
	v_rcp_f32_e32 v58, v58
	v_rcp_f32_e32 v59, v59
	s_nop 0
	v_pk_mul_f32 v[38:39], v[38:39], v[54:55]
	v_pk_mul_f32 v[36:37], v[36:37], v[56:57]
	v_pk_mul_f32 v[40:41], v[34:35], v[58:59]
	v_pk_mul_f32 v[34:35], v[32:33], v[48:49]
	v_cvt_pk_bf16_f32 v32, v36, v37
	v_cvt_pk_bf16_f32 v33, v38, v39
	v_cvt_pk_bf16_f32 v34, v34, v35
	v_cvt_pk_bf16_f32 v35, v40, v41
	global_store_dwordx4 v[52:53], v[32:35], off offset:2048
	s_nop 1
	v_mul_f32_e32 v32, 0xbfb8aa3b, v175
	v_pk_mul_f32 v[38:39], v[28:29], v[32:33] op_sel_hi:[1,0]
	v_pk_mul_f32 v[36:37], v[30:31], v[32:33] op_sel_hi:[1,0]
	v_pk_mul_f32 v[40:41], v[26:27], v[32:33] op_sel_hi:[1,0]
	v_pk_mul_f32 v[32:33], v[24:25], v[32:33] op_sel_hi:[1,0]
	v_exp_f32_e32 v38, v38
	v_exp_f32_e32 v39, v39
	v_exp_f32_e32 v36, v36
	v_exp_f32_e32 v37, v37
	v_exp_f32_e32 v32, v32
	v_exp_f32_e32 v40, v40
	v_exp_f32_e32 v41, v41
	v_exp_f32_e32 v33, v33
	v_pk_fma_f32 v[38:39], v[38:39], v[244:245], v[244:245]
	v_pk_fma_f32 v[36:37], v[36:37], v[244:245], v[244:245]
	v_pk_fma_f32 v[40:41], v[40:41], v[244:245], v[244:245]
	v_pk_fma_f32 v[32:33], v[32:33], v[244:245], v[244:245]
	v_rcp_f32_e32 v38, v38
	v_rcp_f32_e32 v39, v39
	v_rcp_f32_e32 v36, v36
	v_rcp_f32_e32 v37, v37
	v_rcp_f32_e32 v32, v32
	v_rcp_f32_e32 v33, v33
	v_rcp_f32_e32 v40, v40
	v_rcp_f32_e32 v41, v41
	s_nop 0
	v_pk_mul_f32 v[20:21], v[20:21], v[38:39]
	v_pk_mul_f32 v[22:23], v[22:23], v[36:37]
	v_pk_mul_f32 v[24:25], v[18:19], v[40:41]
	v_pk_mul_f32 v[18:19], v[16:17], v[32:33]
	v_cvt_pk_bf16_f32 v16, v20, v21
	v_add_co_u32_e32 v20, vcc, s62, v52
	v_cvt_pk_bf16_f32 v17, v22, v23
	v_cvt_pk_bf16_f32 v18, v18, v19
	v_cvt_pk_bf16_f32 v19, v24, v25
	v_addc_co_u32_e32 v21, vcc, 0, v53, vcc
	global_store_dwordx4 v[20:21], v[16:19], off
	s_andn2_b64 vcc, exec, s[0:1]
	s_mov_b64 s[0:1], -1
	v_mul_f32_e32 v16, 0xbfb8aa3b, v151
	v_pk_mul_f32 v[22:23], v[14:15], v[16:17] op_sel_hi:[1,0]
	v_pk_mul_f32 v[24:25], v[12:13], v[16:17] op_sel_hi:[1,0]
	v_pk_mul_f32 v[26:27], v[10:11], v[16:17] op_sel_hi:[1,0]
	v_pk_mul_f32 v[16:17], v[8:9], v[16:17] op_sel_hi:[1,0]
	v_exp_f32_e32 v24, v24
	v_exp_f32_e32 v25, v25
	v_exp_f32_e32 v22, v22
	v_exp_f32_e32 v23, v23
	v_exp_f32_e32 v16, v16
	v_exp_f32_e32 v26, v26
	v_exp_f32_e32 v27, v27
	v_exp_f32_e32 v17, v17
	v_pk_fma_f32 v[22:23], v[22:23], v[246:247], v[246:247]
	v_pk_fma_f32 v[24:25], v[24:25], v[246:247], v[246:247]
	v_pk_fma_f32 v[26:27], v[26:27], v[246:247], v[246:247]
	v_pk_fma_f32 v[16:17], v[16:17], v[246:247], v[246:247]
	v_rcp_f32_e32 v24, v24
	v_rcp_f32_e32 v25, v25
	v_rcp_f32_e32 v22, v22
	v_rcp_f32_e32 v23, v23
	v_rcp_f32_e32 v16, v16
	v_rcp_f32_e32 v17, v17
	v_rcp_f32_e32 v26, v26
	v_rcp_f32_e32 v27, v27
	s_nop 0
	v_pk_mul_f32 v[6:7], v[6:7], v[22:23]
	v_pk_mul_f32 v[4:5], v[4:5], v[24:25]
	v_pk_mul_f32 v[8:9], v[2:3], v[26:27]
	v_pk_mul_f32 v[2:3], v[0:1], v[16:17]
	v_cvt_pk_bf16_f32 v0, v4, v5
	v_cvt_pk_bf16_f32 v1, v6, v7
	v_cvt_pk_bf16_f32 v2, v2, v3
	v_cvt_pk_bf16_f32 v3, v8, v9
	global_store_dwordx4 v[20:21], v[0:3], off offset:2048
	s_cbranch_vccnz .LBB0_813
	s_andn2_b64 vcc, exec, s[4:5]
	s_cbranch_vccnz .LBB0_812
	s_barrier
	s_branch .LBB0_812
